# up-GEMM sequence-edge epilogue: first pass's parameter loads prefetched before the unit's K-loop by edge waves, rest issued early; no exposed round trip left in that epilogue
# baseline (speedup 1.0000x reference)
.LBB0_653:
	s_ashr_i32 s37, s36, 31
	s_lshl_b64 s[10:11], s[36:37], 18
	s_add_u32 s40, s62, s10
	s_addc_u32 s41, s63, s11
	s_waitcnt lgkmcnt(0)
	s_and_b64 s[8:9], s[8:9], exec
	s_cselect_b32 s3, s41, s13
	s_cselect_b32 s16, s40, s12
	s_barrier
	s_setprio 1
	s_waitcnt lgkmcnt(0)
	v_mfma_i32_16x16x64_i8 v[0:3], v[192:195], v[104:107], v[16:19]
	v_mfma_i32_16x16x64_i8 v[76:79], v[196:199], v[224:227], v[0:3]
	v_mfma_i32_16x16x64_i8 v[0:3], v[200:203], v[104:107], v[20:23]
	v_mfma_i32_16x16x64_i8 v[12:15], v[204:207], v[224:227], v[0:3]
	v_mfma_i32_16x16x64_i8 v[0:3], v[192:195], v[100:103], v[24:27]
	v_mfma_i32_16x16x64_i8 v[72:75], v[196:199], v[220:223], v[0:3]
	v_mfma_i32_16x16x64_i8 v[0:3], v[200:203], v[100:103], v[28:31]
	v_mfma_i32_16x16x64_i8 v[8:11], v[204:207], v[220:223], v[0:3]
	v_mfma_i32_16x16x64_i8 v[0:3], v[192:195], v[96:99], v[32:35]
	v_mfma_i32_16x16x64_i8 v[68:71], v[196:199], v[216:219], v[0:3]
	v_mfma_i32_16x16x64_i8 v[0:3], v[200:203], v[96:99], v[36:39]
	v_mfma_i32_16x16x64_i8 v[4:7], v[204:207], v[216:219], v[0:3]
	v_mfma_i32_16x16x64_i8 v[0:3], v[192:195], v[208:211], v[40:43]
	v_mfma_i32_16x16x64_i8 v[64:67], v[196:199], v[212:215], v[0:3]
	v_mfma_i32_16x16x64_i8 v[0:3], v[200:203], v[208:211], v[44:47]
	v_mfma_i32_16x16x64_i8 v[0:3], v[204:207], v[212:215], v[0:3]
	s_setprio 0
	s_setprio 1
	v_mfma_i32_16x16x64_i8 v[16:19], v[176:179], v[104:107], v[48:51]
	v_mfma_i32_16x16x64_i8 v[108:111], v[180:183], v[224:227], v[16:19]
	v_mfma_i32_16x16x64_i8 v[16:19], v[184:187], v[104:107], v[52:55]
	v_mfma_i32_16x16x64_i8 v[44:47], v[188:191], v[224:227], v[16:19]
	v_mfma_i32_16x16x64_i8 v[16:19], v[176:179], v[100:103], v[56:59]
	v_mfma_i32_16x16x64_i8 v[104:107], v[180:183], v[220:223], v[16:19]
	v_mfma_i32_16x16x64_i8 v[16:19], v[184:187], v[100:103], v[60:63]
	v_mfma_i32_16x16x64_i8 v[40:43], v[188:191], v[220:223], v[16:19]
	v_mfma_i32_16x16x64_i8 v[16:19], v[176:179], v[96:99], v[80:83]
	v_mfma_i32_16x16x64_i8 v[100:103], v[180:183], v[216:219], v[16:19]
	v_mfma_i32_16x16x64_i8 v[16:19], v[184:187], v[96:99], v[84:87]
	v_mfma_i32_16x16x64_i8 v[36:39], v[188:191], v[216:219], v[16:19]
	v_mfma_i32_16x16x64_i8 v[16:19], v[176:179], v[208:211], v[88:91]
	v_mfma_i32_16x16x64_i8 v[96:99], v[180:183], v[212:215], v[16:19]
	v_mfma_i32_16x16x64_i8 v[16:19], v[184:187], v[208:211], v[92:95]
	v_mfma_i32_16x16x64_i8 v[32:35], v[188:191], v[212:215], v[16:19]
	s_setprio 0
	s_barrier
	s_mov_b64 s[10:11], 0x180
	s_mov_b32 m0, s74
	s_nop 2
	v_lshl_add_u64 v[16:17], v[242:243], 0, s[10:11]
	s_add_u32 s8, s12, 0x20180
	ds_read_b128 v[48:51], v228 offset:49152
	ds_read_b128 v[52:55], v228 offset:50176
	ds_read_b128 v[56:59], v228 offset:51200
	ds_read_b128 v[208:211], v228 offset:52224
	ds_read_b128 v[212:215], v228 offset:53248
	ds_read_b128 v[216:219], v228 offset:54272
	ds_read_b128 v[220:223], v228 offset:55296
	ds_read_b128 v[224:227], v228 offset:56320
	global_load_lds_dwordx4 v[16:17], off
	v_lshl_add_u64 v[16:17], v[248:249], 0, s[10:11]
	s_mov_b32 m0, s75
	s_addc_u32 s9, s13, 0
	global_load_lds_dwordx4 v[16:17], off
	v_lshl_add_u64 v[16:17], s[8:9], 0, v[236:237]
	s_mov_b32 m0, s4
	s_nop 0
	global_load_lds_dwordx4 v[16:17], off
	v_lshl_add_u64 v[16:17], s[8:9], 0, v[240:241]
	s_mov_b32 m0, s5
	s_nop 0
	global_load_lds_dwordx4 v[16:17], off
	v_lshl_add_u64 v[16:17], v[244:245], 0, s[10:11]
	s_mov_b32 m0, s76
	s_nop 0
	global_load_lds_dwordx4 v[16:17], off
	v_lshl_add_u64 v[16:17], v[246:247], 0, s[10:11]
	s_mov_b32 m0, s77
	s_nop 0
	global_load_lds_dwordx4 v[16:17], off
	s_waitcnt vmcnt(8)
	s_waitcnt lgkmcnt(0)
	s_barrier
	s_setprio 1
	s_waitcnt lgkmcnt(0)
	v_mfma_i32_16x16x64_i8 v[16:19], v[192:195], v[48:51], v[112:115]
	v_mfma_i32_16x16x64_i8 v[92:95], v[196:199], v[52:55], v[16:19]
	v_mfma_i32_16x16x64_i8 v[16:19], v[200:203], v[48:51], v[116:119]
	v_mfma_i32_16x16x64_i8 v[28:31], v[204:207], v[52:55], v[16:19]
	v_mfma_i32_16x16x64_i8 v[16:19], v[192:195], v[56:59], v[120:123]
	v_mfma_i32_16x16x64_i8 v[88:91], v[196:199], v[208:211], v[16:19]
	v_mfma_i32_16x16x64_i8 v[16:19], v[200:203], v[56:59], v[124:127]
	v_mfma_i32_16x16x64_i8 v[24:27], v[204:207], v[208:211], v[16:19]
	v_mfma_i32_16x16x64_i8 v[16:19], v[192:195], v[212:215], v[128:131]
	v_mfma_i32_16x16x64_i8 v[84:87], v[196:199], v[216:219], v[16:19]
	v_mfma_i32_16x16x64_i8 v[16:19], v[200:203], v[212:215], v[132:135]
	v_mfma_i32_16x16x64_i8 v[20:23], v[204:207], v[216:219], v[16:19]
	v_mfma_i32_16x16x64_i8 v[16:19], v[192:195], v[220:223], v[136:139]
	v_mfma_i32_16x16x64_i8 v[80:83], v[196:199], v[224:227], v[16:19]
	v_mfma_i32_16x16x64_i8 v[16:19], v[200:203], v[220:223], v[140:143]
	v_mfma_i32_16x16x64_i8 v[16:19], v[204:207], v[224:227], v[16:19]
	s_setprio 0
	s_setprio 1
	v_mfma_i32_16x16x64_i8 v[60:63], v[176:179], v[48:51], v[144:147]
	v_mfma_i32_16x16x64_i8 v[48:51], v[184:187], v[48:51], v[148:151]
	v_mfma_i32_16x16x64_i8 v[124:127], v[180:183], v[52:55], v[60:63]
	v_mfma_i32_16x16x64_i8 v[60:63], v[188:191], v[52:55], v[48:51]
	v_mfma_i32_16x16x64_i8 v[48:51], v[176:179], v[56:59], v[152:155]
	v_mfma_i32_16x16x64_i8 v[120:123], v[180:183], v[208:211], v[48:51]
	v_mfma_i32_16x16x64_i8 v[48:51], v[184:187], v[56:59], v[156:159]
	v_mfma_i32_16x16x64_i8 v[56:59], v[188:191], v[208:211], v[48:51]
	v_mfma_i32_16x16x64_i8 v[48:51], v[176:179], v[212:215], v[160:163]
	v_mfma_i32_16x16x64_i8 v[116:119], v[180:183], v[216:219], v[48:51]
	v_mfma_i32_16x16x64_i8 v[48:51], v[184:187], v[212:215], v[164:167]
	v_mfma_i32_16x16x64_i8 v[52:55], v[188:191], v[216:219], v[48:51]
	v_mfma_i32_16x16x64_i8 v[48:51], v[176:179], v[220:223], v[168:171]
	v_mfma_i32_16x16x64_i8 v[112:115], v[180:183], v[224:227], v[48:51]
	v_mfma_i32_16x16x64_i8 v[48:51], v[184:187], v[220:223], v[172:175]
	v_mfma_i32_16x16x64_i8 v[48:51], v[188:191], v[224:227], v[48:51]
	s_setprio 0
	s_barrier
	s_mul_i32 s100, s19, 0xfc
	s_add_i32 s100, s61, s100
	s_add_i32 s101, s100, 0x1080
	s_and_b32 s101, s101, 0xfffff000
	s_addk_i32 s100, 0x1000
	s_cmp_lt_i32 s101, s100
	s_cbranch_scc1 .Lmy_edge_nopf
	v_mbcnt_lo_u32_b32 v220, -1, 0
	v_mbcnt_hi_u32_b32 v220, -1, v220
	s_lshl_b32 s100, s95, 7
	v_lshrrev_b32_e32 v220, 4, v220
	s_or_b32 s100, s100, s73
	v_lshl_add_u32 v220, v220, 2, s100
	v_lshlrev_b32_e32 v220, 2, v220
	v_add_u32_e32 v224, 0x2c00, v220
	global_load_dwordx4 v[242:245], v220, s[28:29]
	global_load_dwordx4 v[246:249], v220, s[26:27]
	global_load_dwordx4 v[220:223], v224, s[28:29]
	global_load_dwordx4 v[224:227], v224, s[26:27]
.Lmy_edge_nopf:
	s_add_u32 s8, s14, 0x1180
	s_addc_u32 s9, s15, 0
	s_add_u32 s14, s12, 0x200
	s_addc_u32 s15, s13, 0
	s_mov_b32 s17, 0

.LBB0_659:
	s_mul_i32 s3, s19, 0xfc
	s_add_i32 s37, s61, s3
	s_add_i32 s8, s37, 0x1080
	s_ashr_i32 s9, s8, 31
	s_lshr_b32 s9, s9, 20
	s_add_i32 s8, s8, s9
	s_mul_i32 s9, s18, 0x1400
	s_add_i32 s83, s9, 0
	v_cvt_f32_i32_e32 v183, v109
	v_cvt_f32_i32_e32 v182, v108
	v_cvt_f32_i32_e32 v181, v105
	v_cvt_f32_i32_e32 v180, v104
	v_cvt_f32_i32_e32 v179, v101
	v_cvt_f32_i32_e32 v178, v100
	v_cvt_f32_i32_e32 v177, v97
	v_cvt_f32_i32_e32 v176, v96
	v_cvt_f32_i32_e32 v125, v125
	v_cvt_f32_i32_e32 v124, v124
	v_cvt_f32_i32_e32 v121, v121
	v_cvt_f32_i32_e32 v120, v120
	v_cvt_f32_i32_e32 v117, v117
	v_cvt_f32_i32_e32 v116, v116
	v_cvt_f32_i32_e32 v113, v113
	v_cvt_f32_i32_e32 v112, v112
	v_cvt_f32_i32_e32 v109, v77
	v_cvt_f32_i32_e32 v108, v76
	v_cvt_f32_i32_e32 v105, v73
	v_cvt_f32_i32_e32 v104, v72
	v_cvt_f32_i32_e32 v101, v69
	v_cvt_f32_i32_e32 v100, v68
	v_cvt_f32_i32_e32 v97, v65
	v_cvt_f32_i32_e32 v96, v64
	v_cvt_f32_i32_e32 v77, v93
	v_cvt_f32_i32_e32 v76, v92
	v_cvt_f32_i32_e32 v73, v89
	v_cvt_f32_i32_e32 v72, v88
	v_cvt_f32_i32_e32 v69, v85
	v_cvt_f32_i32_e32 v68, v84
	v_cvt_f32_i32_e32 v65, v81
	v_cvt_f32_i32_e32 v64, v80
	s_add_i32 s83, s83, 0x20340
	s_lshl_b32 s9, s60, 2
	s_add_i32 s3, s37, 0x1000
	s_and_b32 s8, s8, 0xfffff000
	s_add_i32 s33, s83, s9
	s_cmp_lt_i32 s8, s3
	s_cbranch_scc1 .LBB0_685
	v_mbcnt_lo_u32_b32 v80, -1, 0
	v_mbcnt_hi_u32_b32 v80, -1, v80
	s_lshl_b32 s3, s95, 7
	v_and_b32_e32 v81, 15, v80
	v_ashrrev_i32_e32 v84, 4, v80
	s_or_b32 s3, s3, s73
	v_lshl_add_u32 v80, v81, 5, s33
	v_add_u32_e32 v85, 0x1000, v80
	v_add_u32_e32 v80, 0x1010, v80
	ds_read2_b64 v[132:135], v85 offset1:1
	ds_read2_b64 v[128:131], v80 offset1:1
	v_lshl_add_u32 v80, v84, 2, s3
	s_lshl_b32 s3, s73, 2
	v_lshlrev_b32_e32 v185, 3, v81
	v_ashrrev_i32_e32 v81, 31, v80
	s_add_i32 s3, s83, s3
	v_lshlrev_b64 v[88:89], 2, v[80:81]
	s_mov_b64 s[8:9], 0x2c00
	v_lshl_add_u32 v202, v84, 4, s3
	v_lshl_add_u64 v[92:93], v[88:89], 0, s[8:9]
	v_add_u32_e32 v196, 0x800, v202
	v_lshl_add_u64 v[152:153], s[28:29], 0, v[92:93]
	ds_read2_b64 v[136:139], v196 offset1:1
	ds_read2_b64 v[144:147], v196 offset0:64 offset1:65
	ds_read2_b64 v[140:143], v196 offset0:128 offset1:129
	ds_read2_b64 v[148:151], v196 offset0:192 offset1:193
	v_mov_b32_e32 v152, v220
	v_mov_b32_e32 v153, v221
	v_mov_b32_e32 v92, v224
	v_mov_b32_e32 v93, v225
	s_mov_b32 s42, 0x3c010204
	v_add_u32_e32 v85, s37, v185
	v_and_b32_e32 v171, 0xfff, v85
	s_movk_i32 s3, 0xfff
	s_waitcnt lgkmcnt(0)
	v_pk_mul_f32 v[166:167], v[132:133], v[182:183] op_sel_hi:[0,1]
	v_pk_mul_f32 v[168:169], v[132:133], v[180:181] op_sel:[1,0]
	v_pk_fma_f32 v[174:175], v[144:145], v[166:167], v[148:149]
	v_pk_mul_f32 v[162:163], v[134:135], v[178:179] op_sel_hi:[0,1]
	v_mov_b32_e32 v184, v135
	v_pk_mul_f32 v[160:161], v[184:185], v[176:177] op_sel_hi:[0,1]
	v_pk_mul_f32 v[158:159], v[128:129], v[124:125] op_sel_hi:[0,1]
	s_mov_b32 s24, 0x3856241d
	v_pk_mul_f32 v[198:199], v[134:135], v[100:101] op_sel_hi:[0,1]
	v_pk_mul_f32 v[200:201], v[184:185], v[96:97] op_sel_hi:[0,1]
	v_pk_mul_f32 v[204:205], v[128:129], v[76:77] op_sel_hi:[0,1]
	v_pk_mul_f32 v[206:207], v[128:129], v[72:73] op_sel:[1,0]
	v_pk_mul_f32 v[208:209], v[130:131], v[68:69] op_sel_hi:[0,1]
	v_max_f32_e32 v81, v152, v152
	v_max_f32_e32 v152, 0xda24260, v81
	v_max_f32_e32 v81, v153, v153
	v_max_f32_e32 v153, 0xda24260, v81
	v_pk_add_f32 v[92:93], v[92:93], 0 neg_lo:[1,1] neg_hi:[1,1]
	v_pk_mul_f32 v[152:153], v[152:153], s[42:43] op_sel_hi:[1,0]
	s_nop 0
	v_div_scale_f32 v81, s[8:9], v152, v152, v92
	v_rcp_f32_e32 v84, v81
	s_nop 0
	v_fma_f32 v154, -v81, v84, 1.0
	v_fmac_f32_e32 v84, v154, v84
	v_div_scale_f32 v154, vcc, v92, v152, v92
	v_mul_f32_e32 v155, v154, v84
	v_fma_f32 v156, -v81, v155, v154
	v_fmac_f32_e32 v155, v156, v84
	v_fma_f32 v81, -v81, v155, v154
	v_div_fmas_f32 v81, v81, v84, v155
	v_div_scale_f32 v84, s[8:9], v153, v153, v93
	v_div_fixup_f32 v81, v81, v152, v92
	v_rcp_f32_e32 v92, v84
	v_cmp_eq_u32_e64 s[8:9], s3, v171
	v_add_u32_e32 v171, 1, v85
	v_and_b32_e32 v171, 0xffe, v171
	v_fma_f32 v152, -v84, v92, 1.0
	v_fmac_f32_e32 v92, v152, v92
	v_div_scale_f32 v152, vcc, v93, v153, v93
	v_mul_f32_e32 v154, v152, v92
	v_fma_f32 v155, -v84, v154, v152
	v_fmac_f32_e32 v154, v155, v92
	v_fma_f32 v84, -v84, v154, v152
	v_cmp_eq_u32_e64 s[10:11], 0, v171
	v_sub_u32_e32 v171, 0xffd, v85
	v_div_fmas_f32 v84, v84, v92, v154
	v_and_b32_e32 v171, 0xffe, v171
	v_div_fixup_f32 v170, v84, v153, v93
	v_mov_b32_e32 v84, v131
	v_cmp_eq_u32_e64 s[12:13], 0, v171
	v_add_u32_e32 v171, 3, v85
	v_pk_mul_f32 v[92:93], v[84:85], v[112:113] op_sel_hi:[0,1]
	v_and_b32_e32 v171, 0xffe, v171
	v_mov_b32_e32 v164, v92
	v_mov_b32_e32 v165, v93
	v_cmp_eq_u32_e64 s[14:15], 0, v171
	v_sub_u32_e32 v171, 0xffb, v85
	v_mov_b32_dpp v164, v164 row_shr:1 row_mask:0xf bank_mask:0xf
	v_mov_b32_dpp v165, v165 row_shr:1 row_mask:0xf bank_mask:0xf
	v_and_b32_e32 v171, 0xffe, v171
	v_cndmask_b32_e64 v173, v169, v170, s[8:9]
	v_cndmask_b32_e64 v172, v168, v81, s[8:9]
	v_pk_fma_f32 v[164:165], v[136:137], v[164:165], v[174:175]
	v_cmp_eq_u32_e64 s[22:23], 0, v171
	v_add_u32_e32 v171, 5, v85
	v_mov_b32_e32 v154, v166
	v_mov_b32_e32 v155, v167
	v_pk_fma_f32 v[164:165], v[140:141], v[172:173], v[164:165]
	v_cndmask_b32_e64 v167, v167, v170, s[10:11]
	v_cndmask_b32_e64 v166, v166, v81, s[10:11]
	v_pk_fma_f32 v[172:173], v[144:145], v[168:169], v[148:149]
	v_pk_fma_f32 v[174:175], v[144:145], v[162:163], v[148:149]
	v_and_b32_e32 v171, 0xffe, v171
	v_pk_fma_f32 v[166:167], v[136:137], v[166:167], v[172:173]
	v_cndmask_b32_e64 v173, v161, v170, s[12:13]
	v_cndmask_b32_e64 v172, v160, v81, s[12:13]
	v_pk_fma_f32 v[168:169], v[136:137], v[168:169], v[174:175]
	v_cmp_eq_u32_e64 s[20:21], 0, v171
	v_sub_u32_e32 v171, 0xff9, v85
	v_pk_mul_f32 v[156:157], v[128:129], v[120:121] op_sel:[1,0]
	v_pk_fma_f32 v[166:167], v[140:141], v[162:163], v[166:167]
	v_pk_fma_f32 v[168:169], v[140:141], v[172:173], v[168:169]
	v_cndmask_b32_e64 v163, v163, v170, s[14:15]
	v_cndmask_b32_e64 v162, v162, v81, s[14:15]
	v_pk_fma_f32 v[172:173], v[144:145], v[160:161], v[148:149]
	v_pk_fma_f32 v[174:175], v[144:145], v[158:159], v[148:149]
	v_and_b32_e32 v171, 0xffe, v171
	v_pk_fma_f32 v[162:163], v[136:137], v[162:163], v[172:173]
	v_cndmask_b32_e64 v173, v157, v170, s[22:23]
	v_cndmask_b32_e64 v172, v156, v81, s[22:23]
	v_pk_fma_f32 v[160:161], v[136:137], v[160:161], v[174:175]
	v_cmp_eq_u32_e64 s[18:19], 0, v171
	v_add_u32_e32 v171, 7, v85
	v_pk_fma_f32 v[162:163], v[140:141], v[158:159], v[162:163]
	v_pk_fma_f32 v[160:161], v[140:141], v[172:173], v[160:161]
	v_cndmask_b32_e64 v159, v159, v170, s[20:21]
	v_cndmask_b32_e64 v158, v158, v81, s[20:21]
	v_pk_fma_f32 v[172:173], v[144:145], v[156:157], v[148:149]
	v_and_b32_e32 v171, 0xffe, v171
	v_pk_mul_f32 v[152:153], v[130:131], v[116:117] op_sel_hi:[0,1]
	v_pk_fma_f32 v[158:159], v[136:137], v[158:159], v[172:173]
	v_cmp_eq_u32_e64 s[16:17], 0, v171
	v_pk_fma_f32 v[158:159], v[140:141], v[152:153], v[158:159]
	v_cndmask_b32_e64 v173, v93, v170, s[18:19]
	v_cndmask_b32_e64 v172, v92, v81, s[18:19]
	v_pk_fma_f32 v[174:175], v[144:145], v[152:153], v[148:149]
	v_cndmask_b32_e64 v153, v153, v170, s[16:17]
	v_cndmask_b32_e64 v152, v152, v81, s[16:17]
	v_pk_fma_f32 v[92:93], v[144:145], v[92:93], v[148:149]
	v_mov_b32_dpp v154, v154 row_shl:1 row_mask:0xf bank_mask:0xf
	v_mov_b32_dpp v155, v155 row_shl:1 row_mask:0xf bank_mask:0xf
	v_pk_fma_f32 v[156:157], v[136:137], v[156:157], v[174:175]
	v_pk_fma_f32 v[92:93], v[136:137], v[152:153], v[92:93]
	v_pk_fma_f32 v[156:157], v[140:141], v[172:173], v[156:157]
	v_pk_fma_f32 v[92:93], v[140:141], v[154:155], v[92:93]
	v_and_b32_e32 v141, 0x7fffffff, v165
	v_and_b32_e32 v140, 0x7fffffff, v164
	v_mov_b64_e32 v[136:137], s[24:25]
	v_pk_fma_f32 v[144:145], v[140:141], s[80:81], v[136:137] op_sel_hi:[1,0,0]
	v_and_b32_e32 v149, 0x7fffffff, v167
	v_pk_fma_f32 v[144:145], v[140:141], v[144:145], s[84:85] op_sel_hi:[1,1,0]
	v_and_b32_e32 v148, 0x7fffffff, v166
	v_pk_fma_f32 v[144:145], v[140:141], v[144:145], s[86:87] op_sel_hi:[1,1,0]
	v_pk_fma_f32 v[186:187], v[148:149], s[80:81], v[136:137] op_sel_hi:[1,0,0]
	v_pk_fma_f32 v[144:145], v[140:141], v[144:145], s[82:83] op_sel_hi:[1,1,0]
	v_pk_fma_f32 v[186:187], v[148:149], v[186:187], s[84:85] op_sel_hi:[1,1,0]
	v_pk_fma_f32 v[144:145], v[140:141], v[144:145], s[94:95] op_sel_hi:[1,1,0]
	v_pk_fma_f32 v[186:187], v[148:149], v[186:187], s[86:87] op_sel_hi:[1,1,0]
	v_pk_fma_f32 v[144:145], v[140:141], v[144:145], s[92:93] op_sel_hi:[1,1,0]
	v_and_b32_e32 v175, 0x7fffffff, v169
	v_pk_mul_f32 v[144:145], v[144:145], v[144:145]
	v_and_b32_e32 v174, 0x7fffffff, v168
	v_pk_fma_f32 v[186:187], v[148:149], v[186:187], s[82:83] op_sel_hi:[1,1,0]
	v_pk_mul_f32 v[144:145], v[144:145], v[144:145]
	v_pk_fma_f32 v[188:189], v[174:175], s[80:81], v[136:137] op_sel_hi:[1,0,0]
	v_pk_fma_f32 v[186:187], v[148:149], v[186:187], s[94:95] op_sel_hi:[1,1,0]
	v_pk_mul_f32 v[144:145], v[144:145], v[144:145]
	v_pk_fma_f32 v[188:189], v[174:175], v[188:189], s[84:85] op_sel_hi:[1,1,0]
	v_pk_fma_f32 v[186:187], v[148:149], v[186:187], s[92:93] op_sel_hi:[1,1,0]
	v_pk_mul_f32 v[144:145], v[144:145], v[144:145]
	v_pk_fma_f32 v[188:189], v[174:175], v[188:189], s[86:87] op_sel_hi:[1,1,0]
	v_pk_mul_f32 v[186:187], v[186:187], v[186:187]
	v_rcp_f32_e32 v144, v144
	v_rcp_f32_e32 v145, v145
	v_and_b32_e32 v173, 0x7fffffff, v163
	v_and_b32_e32 v172, 0x7fffffff, v162
	v_pk_fma_f32 v[188:189], v[174:175], v[188:189], s[82:83] op_sel_hi:[1,1,0]
	v_pk_mul_f32 v[186:187], v[186:187], v[186:187]
	v_pk_fma_f32 v[190:191], v[172:173], s[80:81], v[136:137] op_sel_hi:[1,0,0]
	v_pk_fma_f32 v[188:189], v[174:175], v[188:189], s[94:95] op_sel_hi:[1,1,0]
	v_pk_mul_f32 v[186:187], v[186:187], v[186:187]
	v_pk_fma_f32 v[190:191], v[172:173], v[190:191], s[84:85] op_sel_hi:[1,1,0]
	v_pk_fma_f32 v[188:189], v[174:175], v[188:189], s[92:93] op_sel_hi:[1,1,0]
	v_pk_mul_f32 v[192:193], v[186:187], v[186:187]
	v_max_f32_e32 v165, 0, v165
	v_max_f32_e32 v164, 0, v164
	v_pk_fma_f32 v[190:191], v[172:173], v[190:191], s[86:87] op_sel_hi:[1,1,0]
	v_pk_mul_f32 v[188:189], v[188:189], v[188:189]
	v_pk_fma_f32 v[186:187], v[140:141], v[144:145], v[164:165] neg_lo:[1,0,0] neg_hi:[1,0,0]
	v_rcp_f32_e32 v140, v192
	v_rcp_f32_e32 v141, v193
	v_pk_fma_f32 v[190:191], v[172:173], v[190:191], s[82:83] op_sel_hi:[1,1,0]
	v_pk_mul_f32 v[188:189], v[188:189], v[188:189]
	v_pk_fma_f32 v[190:191], v[172:173], v[190:191], s[94:95] op_sel_hi:[1,1,0]
	v_pk_mul_f32 v[188:189], v[188:189], v[188:189]
	v_pk_fma_f32 v[190:191], v[172:173], v[190:191], s[92:93] op_sel_hi:[1,1,0]
	v_pk_mul_f32 v[188:189], v[188:189], v[188:189]
	v_max_f32_e32 v145, 0, v167
	v_max_f32_e32 v144, 0, v166
	v_pk_mul_f32 v[190:191], v[190:191], v[190:191]
	v_pk_fma_f32 v[148:149], v[148:149], v[140:141], v[144:145] neg_lo:[1,0,0] neg_hi:[1,0,0]
	v_rcp_f32_e32 v140, v188
	v_rcp_f32_e32 v141, v189
	v_pk_mul_f32 v[190:191], v[190:191], v[190:191]
	v_max_f32_e32 v145, 0, v169
	v_pk_mul_f32 v[190:191], v[190:191], v[190:191]
	v_max_f32_e32 v144, 0, v168
	v_pk_mul_f32 v[190:191], v[190:191], v[190:191]
	v_pk_fma_f32 v[144:145], v[174:175], v[140:141], v[144:145] neg_lo:[1,0,0] neg_hi:[1,0,0]
	v_rcp_f32_e32 v140, v190
	v_rcp_f32_e32 v141, v191
	v_max_f32_e32 v163, 0, v163
	v_max_f32_e32 v162, 0, v162
	v_and_b32_e32 v171, 0x7fffffff, v159
	v_pk_fma_f32 v[140:141], v[172:173], v[140:141], v[162:163] neg_lo:[1,0,0] neg_hi:[1,0,0]
	v_and_b32_e32 v163, 0x7fffffff, v161
	v_and_b32_e32 v162, 0x7fffffff, v160
	v_pk_fma_f32 v[164:165], v[162:163], s[80:81], v[136:137] op_sel_hi:[1,0,0]
	v_and_b32_e32 v170, 0x7fffffff, v158
	v_pk_fma_f32 v[164:165], v[162:163], v[164:165], s[84:85] op_sel_hi:[1,1,0]
	v_pk_fma_f32 v[166:167], v[170:171], s[80:81], v[136:137] op_sel_hi:[1,0,0]
	v_pk_fma_f32 v[164:165], v[162:163], v[164:165], s[86:87] op_sel_hi:[1,1,0]
	v_pk_fma_f32 v[166:167], v[170:171], v[166:167], s[84:85] op_sel_hi:[1,1,0]
	v_pk_fma_f32 v[164:165], v[162:163], v[164:165], s[82:83] op_sel_hi:[1,1,0]
	v_pk_fma_f32 v[166:167], v[170:171], v[166:167], s[86:87] op_sel_hi:[1,1,0]
	v_pk_fma_f32 v[164:165], v[162:163], v[164:165], s[94:95] op_sel_hi:[1,1,0]
	v_and_b32_e32 v155, 0x7fffffff, v157
	v_pk_fma_f32 v[164:165], v[162:163], v[164:165], s[92:93] op_sel_hi:[1,1,0]
	v_and_b32_e32 v154, 0x7fffffff, v156
	v_pk_mul_f32 v[164:165], v[164:165], v[164:165]
	v_pk_fma_f32 v[166:167], v[170:171], v[166:167], s[82:83] op_sel_hi:[1,1,0]
	v_pk_mul_f32 v[164:165], v[164:165], v[164:165]
	v_pk_fma_f32 v[168:169], v[154:155], s[80:81], v[136:137] op_sel_hi:[1,0,0]
	v_pk_fma_f32 v[166:167], v[170:171], v[166:167], s[94:95] op_sel_hi:[1,1,0]
	v_pk_mul_f32 v[164:165], v[164:165], v[164:165]
	v_pk_fma_f32 v[168:169], v[154:155], v[168:169], s[84:85] op_sel_hi:[1,1,0]
	v_pk_fma_f32 v[166:167], v[170:171], v[166:167], s[92:93] op_sel_hi:[1,1,0]
	v_pk_mul_f32 v[164:165], v[164:165], v[164:165]
	v_pk_fma_f32 v[168:169], v[154:155], v[168:169], s[86:87] op_sel_hi:[1,1,0]
	v_pk_mul_f32 v[166:167], v[166:167], v[166:167]
	v_rcp_f32_e32 v164, v164
	v_rcp_f32_e32 v165, v165
	v_and_b32_e32 v153, 0x7fffffff, v93
	v_and_b32_e32 v152, 0x7fffffff, v92
	v_pk_fma_f32 v[168:169], v[154:155], v[168:169], s[82:83] op_sel_hi:[1,1,0]
	v_pk_mul_f32 v[166:167], v[166:167], v[166:167]
	v_pk_fma_f32 v[172:173], v[152:153], s[80:81], v[136:137] op_sel_hi:[1,0,0]
	v_pk_fma_f32 v[168:169], v[154:155], v[168:169], s[94:95] op_sel_hi:[1,1,0]
	v_pk_mul_f32 v[166:167], v[166:167], v[166:167]
	v_pk_fma_f32 v[172:173], v[152:153], v[172:173], s[84:85] op_sel_hi:[1,1,0]
	v_pk_fma_f32 v[168:169], v[154:155], v[168:169], s[92:93] op_sel_hi:[1,1,0]
	v_pk_mul_f32 v[166:167], v[166:167], v[166:167]
	v_max_f32_e32 v161, 0, v161
	v_max_f32_e32 v160, 0, v160
	v_pk_fma_f32 v[172:173], v[152:153], v[172:173], s[86:87] op_sel_hi:[1,1,0]
	v_pk_mul_f32 v[168:169], v[168:169], v[168:169]
	v_pk_fma_f32 v[194:195], v[162:163], v[164:165], v[160:161] neg_lo:[1,0,0] neg_hi:[1,0,0]
	v_rcp_f32_e32 v160, v166
	v_rcp_f32_e32 v161, v167
	v_pk_fma_f32 v[172:173], v[152:153], v[172:173], s[82:83] op_sel_hi:[1,1,0]
	v_pk_mul_f32 v[168:169], v[168:169], v[168:169]
	v_pk_fma_f32 v[172:173], v[152:153], v[172:173], s[94:95] op_sel_hi:[1,1,0]
	v_pk_mul_f32 v[168:169], v[168:169], v[168:169]
	v_pk_fma_f32 v[172:173], v[152:153], v[172:173], s[92:93] op_sel_hi:[1,1,0]
	v_pk_mul_f32 v[168:169], v[168:169], v[168:169]
	v_max_f32_e32 v159, 0, v159
	v_max_f32_e32 v158, 0, v158
	v_pk_mul_f32 v[172:173], v[172:173], v[172:173]
	v_pk_fma_f32 v[192:193], v[170:171], v[160:161], v[158:159] neg_lo:[1,0,0] neg_hi:[1,0,0]
	v_rcp_f32_e32 v158, v168
	v_rcp_f32_e32 v159, v169
	v_pk_mul_f32 v[172:173], v[172:173], v[172:173]
	v_max_f32_e32 v157, 0, v157
	v_pk_mul_f32 v[172:173], v[172:173], v[172:173]
	v_max_f32_e32 v156, 0, v156
	v_pk_mul_f32 v[172:173], v[172:173], v[172:173]
	v_pk_fma_f32 v[190:191], v[154:155], v[158:159], v[156:157] neg_lo:[1,0,0] neg_hi:[1,0,0]
	v_rcp_f32_e32 v154, v172
	v_rcp_f32_e32 v155, v173
	v_max_f32_e32 v93, 0, v93
	v_max_f32_e32 v92, 0, v92
	v_pk_mul_f32 v[210:211], v[84:85], v[64:65] op_sel_hi:[0,1]
	v_pk_fma_f32 v[188:189], v[152:153], v[154:155], v[92:93] neg_lo:[1,0,0] neg_hi:[1,0,0]
	v_lshl_add_u64 v[92:93], s[28:29], 0, v[88:89]
	ds_read2_b64 v[156:159], v202 offset0:64 offset1:65
	ds_read2_b64 v[152:155], v202 offset0:128 offset1:129
	ds_read2_b64 v[160:163], v202 offset0:192 offset1:193
	v_mov_b64_e32 v[164:165], v[242:243]
	v_mov_b64_e32 v[166:167], v[244:245]
	v_lshl_add_u64 v[88:89], s[26:27], 0, v[88:89]
	v_mov_b64_e32 v[168:169], v[246:247]
	v_mov_b64_e32 v[170:171], v[248:249]
	v_mov_b32_e32 v212, v210
	v_mov_b32_e32 v213, v211
	s_movk_i32 s3, 0x2000
	v_mov_b32_dpp v212, v212 row_shr:1 row_mask:0xf bank_mask:0xf
	v_mov_b32_dpp v213, v213 row_shr:1 row_mask:0xf bank_mask:0xf
	v_max_f32_e32 v81, v164, v164
	v_max_f32_e32 v164, 0xda24260, v81
	v_max_f32_e32 v81, v165, v165
	v_max_f32_e32 v165, 0xda24260, v81
	v_pk_add_f32 v[168:169], v[168:169], 0 neg_lo:[1,1] neg_hi:[1,1]
	v_pk_mul_f32 v[164:165], v[164:165], s[42:43] op_sel_hi:[1,0]
	s_nop 0
	v_div_scale_f32 v81, s[24:25], v164, v164, v168
	v_rcp_f32_e32 v172, v81
	s_nop 0
	v_fma_f32 v173, -v81, v172, 1.0
	v_fmac_f32_e32 v172, v173, v172
	v_div_scale_f32 v173, vcc, v168, v164, v168
	v_mul_f32_e32 v174, v173, v172
	v_fma_f32 v175, -v81, v174, v173
	v_fmac_f32_e32 v174, v175, v172
	v_fma_f32 v81, -v81, v174, v173
	v_div_fmas_f32 v81, v81, v172, v174
	v_div_fixup_f32 v81, v81, v164, v168
	v_div_scale_f32 v164, s[24:25], v165, v165, v169
	v_rcp_f32_e32 v168, v164
	s_nop 0
	v_fma_f32 v172, -v164, v168, 1.0
	v_fmac_f32_e32 v168, v172, v168
	v_div_scale_f32 v172, vcc, v169, v165, v169
	v_mul_f32_e32 v173, v172, v168
	v_fma_f32 v174, -v164, v173, v172
	v_fmac_f32_e32 v173, v174, v168
	v_fma_f32 v164, -v164, v173, v172
	v_div_fmas_f32 v164, v164, v168, v173
	ds_read2_b64 v[172:175], v202 offset1:1
	v_div_fixup_f32 v203, v164, v165, v169
	v_pk_mul_f32 v[164:165], v[132:133], v[108:109] op_sel_hi:[0,1]
	v_pk_mul_f32 v[168:169], v[132:133], v[104:105] op_sel:[1,0]
	s_waitcnt lgkmcnt(1)
	v_pk_fma_f32 v[218:219], v[156:157], v[164:165], v[160:161]
	v_cndmask_b32_e64 v217, v169, v203, s[8:9]
	v_cndmask_b32_e64 v216, v168, v81, s[8:9]
	s_waitcnt lgkmcnt(0)
	v_pk_fma_f32 v[212:213], v[172:173], v[212:213], v[218:219]
	v_mov_b32_e32 v214, v164
	v_pk_fma_f32 v[212:213], v[152:153], v[216:217], v[212:213]
	v_mov_b32_e32 v215, v165
	v_pk_mul_f32 v[186:187], v[212:213], v[186:187]
	v_cndmask_b32_e64 v165, v165, v203, s[10:11]
	v_cvt_pk_fp8_f32 v197, v186, v187
	s_nop 0
	v_cndmask_b32_e64 v164, v164, v81, s[10:11]
	v_pk_fma_f32 v[186:187], v[156:157], v[168:169], v[160:161]
	v_mov_b32_dpp v214, v214 row_shl:1 row_mask:0xf bank_mask:0xf
	v_pk_fma_f32 v[164:165], v[172:173], v[164:165], v[186:187]
	v_mov_b32_dpp v215, v215 row_shl:1 row_mask:0xf bank_mask:0xf
	v_pk_fma_f32 v[164:165], v[152:153], v[198:199], v[164:165]
	s_nop 0
	v_pk_mul_f32 v[148:149], v[164:165], v[148:149]
	v_pk_fma_f32 v[164:165], v[156:157], v[198:199], v[160:161]
	v_cvt_pk_fp8_f32 v187, v148, v149
	s_nop 0
	v_cndmask_b32_e64 v149, v201, v203, s[12:13]
	v_cndmask_b32_e64 v148, v200, v81, s[12:13]
	v_pk_fma_f32 v[164:165], v[172:173], v[168:169], v[164:165]
	s_nop 0
	v_pk_fma_f32 v[148:149], v[152:153], v[148:149], v[164:165]
	s_nop 0
	v_pk_mul_f32 v[144:145], v[148:149], v[144:145]
	v_pk_fma_f32 v[148:149], v[156:157], v[200:201], v[160:161]
	v_cvt_pk_fp8_f32 v186, v144, v145
	s_nop 0
	v_cndmask_b32_e64 v145, v199, v203, s[14:15]
	v_cndmask_b32_e64 v144, v198, v81, s[14:15]
	v_pk_fma_f32 v[144:145], v[172:173], v[144:145], v[148:149]
	s_nop 0
	v_pk_fma_f32 v[144:145], v[152:153], v[204:205], v[144:145]
	s_nop 0
	v_pk_mul_f32 v[140:141], v[144:145], v[140:141]
	v_pk_fma_f32 v[144:145], v[156:157], v[204:205], v[160:161]
	v_cvt_pk_fp8_f32 v169, v140, v141
	s_nop 0
	v_cndmask_b32_e64 v141, v207, v203, s[22:23]
	v_cndmask_b32_e64 v140, v206, v81, s[22:23]
	v_pk_fma_f32 v[144:145], v[172:173], v[200:201], v[144:145]
	s_nop 0
	v_pk_fma_f32 v[140:141], v[152:153], v[140:141], v[144:145]
	v_pk_fma_f32 v[144:145], v[156:157], v[206:207], v[160:161]
	v_pk_mul_f32 v[140:141], v[140:141], v[194:195]
	s_nop 0
	v_cvt_pk_fp8_f32 v168, v140, v141
	s_nop 0
	v_cndmask_b32_e64 v141, v205, v203, s[20:21]
	v_cndmask_b32_e64 v140, v204, v81, s[20:21]
	v_pk_fma_f32 v[140:141], v[172:173], v[140:141], v[144:145]
	v_pk_fma_f32 v[144:145], v[156:157], v[208:209], v[160:161]
	v_pk_fma_f32 v[140:141], v[152:153], v[208:209], v[140:141]
	v_pk_fma_f32 v[144:145], v[172:173], v[206:207], v[144:145]
	v_pk_mul_f32 v[140:141], v[140:141], v[192:193]
	s_nop 0
	v_cvt_pk_fp8_f32 v165, v140, v141
	s_nop 0
	v_cndmask_b32_e64 v141, v211, v203, s[18:19]
	v_cndmask_b32_e64 v140, v210, v81, s[18:19]
	v_pk_fma_f32 v[140:141], v[152:153], v[140:141], v[144:145]
	v_pk_fma_f32 v[144:145], v[156:157], v[210:211], v[160:161]
	v_pk_mul_f32 v[140:141], v[140:141], v[190:191]
	v_cvt_f32_i32_e32 v157, v127
	v_cvt_pk_fp8_f32 v164, v140, v141
	s_nop 0
	v_cndmask_b32_e64 v141, v209, v203, s[16:17]
	v_cndmask_b32_e64 v140, v208, v81, s[16:17]
	v_pk_fma_f32 v[140:141], v[172:173], v[140:141], v[144:145]
	v_cvt_f32_i32_e32 v161, v123
	v_pk_fma_f32 v[140:141], v[152:153], v[214:215], v[140:141]
	v_cvt_f32_i32_e32 v160, v122
	v_pk_mul_f32 v[140:141], v[140:141], v[188:189]
	v_cvt_f32_i32_e32 v189, v115
	v_cvt_pk_fp8_f32 v81, v140, v141
	s_nop 0
	v_add_co_u32_e32 v140, vcc, s3, v92
	v_cvt_f32_i32_e32 v188, v114
	s_nop 0
	v_addc_co_u32_e32 v141, vcc, 0, v93, vcc
	v_mov_b32_e32 v140, v222
	v_mov_b32_e32 v141, v223
	v_add_co_u32_e32 v144, vcc, s3, v88
	v_pk_mul_f32 v[188:189], v[84:85], v[188:189] op_sel_hi:[0,1]
	s_nop 0
	v_addc_co_u32_e32 v145, vcc, 0, v89, vcc
	v_mov_b32_e32 v144, v226
	v_mov_b32_e32 v145, v227
	v_mov_b32_e32 v190, v188
	v_mov_b32_e32 v191, v189
	v_cvt_f32_i32_e32 v173, v119
	v_mov_b32_dpp v190, v190 row_shr:1 row_mask:0xf bank_mask:0xf
	v_mov_b32_dpp v191, v191 row_shr:1 row_mask:0xf bank_mask:0xf
	v_cvt_f32_i32_e32 v172, v118
	v_pk_mul_f32 v[160:161], v[128:129], v[160:161] op_sel:[1,0]
	s_waitcnt vmcnt(0)
	v_pk_mul_f32 v[172:173], v[130:131], v[172:173] op_sel_hi:[0,1]
	s_waitcnt vmcnt(1)
	v_max_f32_e32 v140, v140, v140
	v_max_f32_e32 v141, v141, v141
	v_max_f32_e32 v140, 0xda24260, v140
	v_max_f32_e32 v141, 0xda24260, v141
	v_pk_mul_f32 v[140:141], v[140:141], s[42:43] op_sel_hi:[1,0]
	s_waitcnt vmcnt(0)
	global_load_dwordx4 v[242:245], v[92:93], off offset:64
	global_load_dwordx4 v[246:249], v[88:89], off offset:64
	v_lshlrev_b32_e32 v227, 2, v80
	v_add_u32_e32 v227, 0x2c40, v227
	global_load_dword v220, v227, s[28:29]
	global_load_dword v237, v227, s[28:29] offset:4
	global_load_dword v241, v227, s[26:27]
	global_load_dword v227, v227, s[26:27] offset:4
	v_pk_add_f32 v[144:145], v[144:145], 0 neg_lo:[1,1] neg_hi:[1,1]
	s_nop 0
	v_div_scale_f32 v148, s[24:25], v140, v140, v144
	v_rcp_f32_e32 v149, v148
	s_nop 0
	v_fma_f32 v152, -v148, v149, 1.0
	v_fmac_f32_e32 v149, v152, v149
	v_div_scale_f32 v152, vcc, v144, v140, v144
	v_mul_f32_e32 v153, v152, v149
	v_fma_f32 v156, -v148, v153, v152
	v_fmac_f32_e32 v153, v156, v149
	v_fma_f32 v148, -v148, v153, v152
	v_div_fmas_f32 v148, v148, v149, v153
	v_div_fixup_f32 v200, v148, v140, v144
	v_div_scale_f32 v140, s[24:25], v141, v141, v145
	v_rcp_f32_e32 v144, v140
	v_cvt_f32_i32_e32 v153, v99
	v_cvt_f32_i32_e32 v156, v126
	v_fma_f32 v148, -v140, v144, 1.0
	v_fmac_f32_e32 v144, v148, v144
	v_div_scale_f32 v148, vcc, v145, v141, v145
	v_mul_f32_e32 v149, v148, v144
	v_fma_f32 v152, -v140, v149, v148
	v_fmac_f32_e32 v149, v152, v144
	v_fma_f32 v140, -v140, v149, v148
	v_div_fmas_f32 v140, v140, v144, v149
	v_div_fixup_f32 v201, v140, v141, v145
	v_cvt_f32_i32_e32 v141, v111
	v_cvt_f32_i32_e32 v140, v110
	v_cvt_f32_i32_e32 v145, v107
	v_cvt_f32_i32_e32 v144, v106
	v_cvt_f32_i32_e32 v149, v103
	v_cvt_f32_i32_e32 v148, v102
	v_cvt_f32_i32_e32 v152, v98
	v_pk_mul_f32 v[140:141], v[132:133], v[140:141] op_sel_hi:[0,1]
	v_pk_mul_f32 v[144:145], v[132:133], v[144:145] op_sel:[1,0]
	v_pk_fma_f32 v[198:199], v[146:147], v[140:141], v[150:151]
	v_pk_mul_f32 v[148:149], v[134:135], v[148:149] op_sel_hi:[0,1]
	v_cndmask_b32_e64 v195, v145, v201, s[8:9]
	v_cndmask_b32_e64 v194, v144, v200, s[8:9]
	v_pk_fma_f32 v[190:191], v[138:139], v[190:191], v[198:199]
	v_pk_mul_f32 v[152:153], v[184:185], v[152:153] op_sel_hi:[0,1]
	v_mov_b32_e32 v192, v140
	v_mov_b32_e32 v193, v141
	v_pk_fma_f32 v[190:191], v[142:143], v[194:195], v[190:191]
	v_cndmask_b32_e64 v141, v141, v201, s[10:11]
	v_cndmask_b32_e64 v140, v140, v200, s[10:11]
	v_pk_fma_f32 v[194:195], v[146:147], v[144:145], v[150:151]
	v_pk_fma_f32 v[198:199], v[146:147], v[148:149], v[150:151]
	v_pk_mul_f32 v[156:157], v[128:129], v[156:157] op_sel_hi:[0,1]
	v_pk_fma_f32 v[140:141], v[138:139], v[140:141], v[194:195]
	v_cndmask_b32_e64 v195, v153, v201, s[12:13]
	v_cndmask_b32_e64 v194, v152, v200, s[12:13]
	v_pk_fma_f32 v[144:145], v[138:139], v[144:145], v[198:199]
	v_pk_fma_f32 v[140:141], v[142:143], v[148:149], v[140:141]
	v_pk_fma_f32 v[144:145], v[142:143], v[194:195], v[144:145]
	v_cndmask_b32_e64 v149, v149, v201, s[14:15]
	v_cndmask_b32_e64 v148, v148, v200, s[14:15]
	v_pk_fma_f32 v[194:195], v[146:147], v[152:153], v[150:151]
	v_pk_fma_f32 v[198:199], v[146:147], v[156:157], v[150:151]
	v_pk_fma_f32 v[148:149], v[138:139], v[148:149], v[194:195]
	v_cndmask_b32_e64 v195, v161, v201, s[22:23]
	v_cndmask_b32_e64 v194, v160, v200, s[22:23]
	v_pk_fma_f32 v[152:153], v[138:139], v[152:153], v[198:199]
	v_pk_fma_f32 v[148:149], v[142:143], v[156:157], v[148:149]
	v_pk_fma_f32 v[152:153], v[142:143], v[194:195], v[152:153]
	v_cndmask_b32_e64 v157, v157, v201, s[20:21]
	v_cndmask_b32_e64 v156, v156, v200, s[20:21]
	v_pk_fma_f32 v[194:195], v[146:147], v[160:161], v[150:151]
	v_pk_fma_f32 v[198:199], v[146:147], v[172:173], v[150:151]
	v_pk_fma_f32 v[156:157], v[138:139], v[156:157], v[194:195]
	v_pk_fma_f32 v[146:147], v[146:147], v[188:189], v[150:151]
	v_pk_fma_f32 v[156:157], v[142:143], v[172:173], v[156:157]
	v_cndmask_b32_e64 v173, v173, v201, s[16:17]
	v_cndmask_b32_e64 v172, v172, v200, s[16:17]
	v_mov_b32_dpp v192, v192 row_shl:1 row_mask:0xf bank_mask:0xf
	v_mov_b32_dpp v193, v193 row_shl:1 row_mask:0xf bank_mask:0xf
	v_pk_fma_f32 v[160:161], v[138:139], v[160:161], v[198:199]
	v_pk_fma_f32 v[138:139], v[138:139], v[172:173], v[146:147]
	v_cndmask_b32_e64 v195, v189, v201, s[18:19]
	v_cndmask_b32_e64 v194, v188, v200, s[18:19]
	v_pk_fma_f32 v[146:147], v[142:143], v[192:193], v[138:139]
	v_and_b32_e32 v139, 0x7fffffff, v191
	v_and_b32_e32 v138, 0x7fffffff, v190
	v_pk_fma_f32 v[160:161], v[142:143], v[194:195], v[160:161]
	v_pk_fma_f32 v[142:143], v[138:139], s[80:81], v[136:137] op_sel_hi:[1,0,0]
	v_and_b32_e32 v199, 0x7fffffff, v141
	v_pk_fma_f32 v[142:143], v[138:139], v[142:143], s[84:85] op_sel_hi:[1,1,0]
	v_and_b32_e32 v198, 0x7fffffff, v140
	v_pk_fma_f32 v[142:143], v[138:139], v[142:143], s[86:87] op_sel_hi:[1,1,0]
	v_pk_fma_f32 v[200:201], v[198:199], s[80:81], v[136:137] op_sel_hi:[1,0,0]
	v_pk_fma_f32 v[142:143], v[138:139], v[142:143], s[82:83] op_sel_hi:[1,1,0]
	v_pk_fma_f32 v[200:201], v[198:199], v[200:201], s[84:85] op_sel_hi:[1,1,0]
	v_pk_fma_f32 v[142:143], v[138:139], v[142:143], s[94:95] op_sel_hi:[1,1,0]
	v_pk_fma_f32 v[200:201], v[198:199], v[200:201], s[86:87] op_sel_hi:[1,1,0]
	v_pk_fma_f32 v[142:143], v[138:139], v[142:143], s[92:93] op_sel_hi:[1,1,0]
	v_and_b32_e32 v195, 0x7fffffff, v145
	v_pk_mul_f32 v[142:143], v[142:143], v[142:143]
	v_and_b32_e32 v194, 0x7fffffff, v144
	v_pk_fma_f32 v[200:201], v[198:199], v[200:201], s[82:83] op_sel_hi:[1,1,0]
	v_pk_mul_f32 v[142:143], v[142:143], v[142:143]
	v_pk_fma_f32 v[204:205], v[194:195], s[80:81], v[136:137] op_sel_hi:[1,0,0]
	v_pk_fma_f32 v[200:201], v[198:199], v[200:201], s[94:95] op_sel_hi:[1,1,0]
	v_pk_mul_f32 v[142:143], v[142:143], v[142:143]
	v_pk_fma_f32 v[204:205], v[194:195], v[204:205], s[84:85] op_sel_hi:[1,1,0]
	v_pk_fma_f32 v[200:201], v[198:199], v[200:201], s[92:93] op_sel_hi:[1,1,0]
	v_pk_mul_f32 v[142:143], v[142:143], v[142:143]
	v_pk_fma_f32 v[204:205], v[194:195], v[204:205], s[86:87] op_sel_hi:[1,1,0]
	v_pk_mul_f32 v[200:201], v[200:201], v[200:201]
	v_rcp_f32_e32 v142, v142
	v_rcp_f32_e32 v143, v143
	v_and_b32_e32 v193, 0x7fffffff, v149
	v_and_b32_e32 v192, 0x7fffffff, v148
	v_pk_fma_f32 v[204:205], v[194:195], v[204:205], s[82:83] op_sel_hi:[1,1,0]
	v_pk_mul_f32 v[200:201], v[200:201], v[200:201]
	v_pk_fma_f32 v[206:207], v[192:193], s[80:81], v[136:137] op_sel_hi:[1,0,0]
	v_pk_fma_f32 v[204:205], v[194:195], v[204:205], s[94:95] op_sel_hi:[1,1,0]
	v_pk_mul_f32 v[200:201], v[200:201], v[200:201]
	v_pk_fma_f32 v[206:207], v[192:193], v[206:207], s[84:85] op_sel_hi:[1,1,0]
	v_pk_fma_f32 v[204:205], v[194:195], v[204:205], s[92:93] op_sel_hi:[1,1,0]
	v_pk_mul_f32 v[200:201], v[200:201], v[200:201]
	v_max_f32_e32 v191, 0, v191
	v_max_f32_e32 v190, 0, v190
	v_pk_fma_f32 v[206:207], v[192:193], v[206:207], s[86:87] op_sel_hi:[1,1,0]
	v_pk_mul_f32 v[204:205], v[204:205], v[204:205]
	v_pk_fma_f32 v[138:139], v[138:139], v[142:143], v[190:191] neg_lo:[1,0,0] neg_hi:[1,0,0]
	v_rcp_f32_e32 v142, v200
	v_rcp_f32_e32 v143, v201
	v_pk_fma_f32 v[206:207], v[192:193], v[206:207], s[82:83] op_sel_hi:[1,1,0]
	v_pk_mul_f32 v[204:205], v[204:205], v[204:205]
	v_pk_fma_f32 v[206:207], v[192:193], v[206:207], s[94:95] op_sel_hi:[1,1,0]
	v_pk_mul_f32 v[204:205], v[204:205], v[204:205]
	v_pk_fma_f32 v[206:207], v[192:193], v[206:207], s[92:93] op_sel_hi:[1,1,0]
	v_pk_mul_f32 v[204:205], v[204:205], v[204:205]
	v_max_f32_e32 v141, 0, v141
	v_max_f32_e32 v140, 0, v140
	v_pk_mul_f32 v[206:207], v[206:207], v[206:207]
	v_pk_fma_f32 v[142:143], v[198:199], v[142:143], v[140:141] neg_lo:[1,0,0] neg_hi:[1,0,0]
	v_rcp_f32_e32 v140, v204
	v_rcp_f32_e32 v141, v205
	v_pk_mul_f32 v[206:207], v[206:207], v[206:207]
	v_max_f32_e32 v145, 0, v145
	v_pk_mul_f32 v[206:207], v[206:207], v[206:207]
	v_max_f32_e32 v144, 0, v144
	v_pk_mul_f32 v[206:207], v[206:207], v[206:207]
	v_pk_fma_f32 v[140:141], v[194:195], v[140:141], v[144:145] neg_lo:[1,0,0] neg_hi:[1,0,0]
	v_rcp_f32_e32 v144, v206
	v_rcp_f32_e32 v145, v207
	v_max_f32_e32 v149, 0, v149
	v_max_f32_e32 v148, 0, v148
	v_and_b32_e32 v173, 0x7fffffff, v147
	v_pk_fma_f32 v[144:145], v[192:193], v[144:145], v[148:149] neg_lo:[1,0,0] neg_hi:[1,0,0]
	v_and_b32_e32 v149, 0x7fffffff, v153
	v_and_b32_e32 v148, 0x7fffffff, v152
	v_and_b32_e32 v172, 0x7fffffff, v146
	v_and_b32_e32 v151, 0x7fffffff, v161
	v_and_b32_e32 v150, 0x7fffffff, v160
	v_and_b32_e32 v189, 0x7fffffff, v157
	v_and_b32_e32 v188, 0x7fffffff, v156
	v_pk_fma_f32 v[190:191], v[148:149], s[80:81], v[136:137] op_sel_hi:[1,0,0]
	v_pk_fma_f32 v[192:193], v[188:189], s[80:81], v[136:137] op_sel_hi:[1,0,0]
	v_pk_fma_f32 v[194:195], v[150:151], s[80:81], v[136:137] op_sel_hi:[1,0,0]
	v_pk_fma_f32 v[136:137], v[172:173], s[80:81], v[136:137] op_sel_hi:[1,0,0]
	v_pk_fma_f32 v[190:191], v[148:149], v[190:191], s[84:85] op_sel_hi:[1,1,0]
	v_pk_fma_f32 v[136:137], v[172:173], v[136:137], s[84:85] op_sel_hi:[1,1,0]
	v_pk_fma_f32 v[190:191], v[148:149], v[190:191], s[86:87] op_sel_hi:[1,1,0]
	v_pk_fma_f32 v[136:137], v[172:173], v[136:137], s[86:87] op_sel_hi:[1,1,0]
	v_pk_fma_f32 v[190:191], v[148:149], v[190:191], s[82:83] op_sel_hi:[1,1,0]
	v_pk_fma_f32 v[136:137], v[172:173], v[136:137], s[82:83] op_sel_hi:[1,1,0]
	v_pk_fma_f32 v[190:191], v[148:149], v[190:191], s[94:95] op_sel_hi:[1,1,0]
	v_pk_fma_f32 v[192:193], v[188:189], v[192:193], s[84:85] op_sel_hi:[1,1,0]
	v_pk_fma_f32 v[136:137], v[172:173], v[136:137], s[94:95] op_sel_hi:[1,1,0]
	v_pk_fma_f32 v[190:191], v[148:149], v[190:191], s[92:93] op_sel_hi:[1,1,0]
	v_pk_fma_f32 v[192:193], v[188:189], v[192:193], s[86:87] op_sel_hi:[1,1,0]
	v_pk_fma_f32 v[136:137], v[172:173], v[136:137], s[92:93] op_sel_hi:[1,1,0]
	v_pk_mul_f32 v[190:191], v[190:191], v[190:191]
	v_pk_fma_f32 v[192:193], v[188:189], v[192:193], s[82:83] op_sel_hi:[1,1,0]
	v_pk_mul_f32 v[136:137], v[136:137], v[136:137]
	v_pk_mul_f32 v[190:191], v[190:191], v[190:191]
	v_pk_fma_f32 v[192:193], v[188:189], v[192:193], s[94:95] op_sel_hi:[1,1,0]
	v_pk_mul_f32 v[136:137], v[136:137], v[136:137]
	v_pk_mul_f32 v[190:191], v[190:191], v[190:191]
	v_pk_fma_f32 v[194:195], v[150:151], v[194:195], s[84:85] op_sel_hi:[1,1,0]
	v_pk_fma_f32 v[192:193], v[188:189], v[192:193], s[92:93] op_sel_hi:[1,1,0]
	v_pk_mul_f32 v[136:137], v[136:137], v[136:137]
	v_pk_mul_f32 v[190:191], v[190:191], v[190:191]
	v_pk_fma_f32 v[194:195], v[150:151], v[194:195], s[86:87] op_sel_hi:[1,1,0]
	v_pk_mul_f32 v[192:193], v[192:193], v[192:193]
	v_pk_mul_f32 v[198:199], v[136:137], v[136:137]
	v_rcp_f32_e32 v136, v190
	v_rcp_f32_e32 v137, v191
	v_pk_fma_f32 v[194:195], v[150:151], v[194:195], s[82:83] op_sel_hi:[1,1,0]
	v_pk_mul_f32 v[192:193], v[192:193], v[192:193]
	v_pk_fma_f32 v[194:195], v[150:151], v[194:195], s[94:95] op_sel_hi:[1,1,0]
	v_pk_mul_f32 v[192:193], v[192:193], v[192:193]
	v_pk_fma_f32 v[194:195], v[150:151], v[194:195], s[92:93] op_sel_hi:[1,1,0]
	v_pk_mul_f32 v[192:193], v[192:193], v[192:193]
	v_max_f32_e32 v153, 0, v153
	v_max_f32_e32 v152, 0, v152
	v_pk_mul_f32 v[194:195], v[194:195], v[194:195]
	v_pk_fma_f32 v[148:149], v[148:149], v[136:137], v[152:153] neg_lo:[1,0,0] neg_hi:[1,0,0]
	v_rcp_f32_e32 v136, v192
	v_rcp_f32_e32 v137, v193
	v_pk_mul_f32 v[194:195], v[194:195], v[194:195]
	v_max_f32_e32 v153, 0, v157
	v_pk_mul_f32 v[194:195], v[194:195], v[194:195]
	v_max_f32_e32 v152, 0, v156
	v_pk_mul_f32 v[194:195], v[194:195], v[194:195]
	v_pk_fma_f32 v[136:137], v[188:189], v[136:137], v[152:153] neg_lo:[1,0,0] neg_hi:[1,0,0]
	v_rcp_f32_e32 v152, v194
	v_rcp_f32_e32 v153, v195
	v_max_f32_e32 v157, 0, v161
	v_max_f32_e32 v156, 0, v160
	v_max_f32_e32 v147, 0, v147
	v_pk_fma_f32 v[150:151], v[150:151], v[152:153], v[156:157] neg_lo:[1,0,0] neg_hi:[1,0,0]
	v_rcp_f32_e32 v152, v198
	v_rcp_f32_e32 v153, v199
	v_max_f32_e32 v146, 0, v146
	v_pk_add_f32 v[156:157], v[170:171], 0 neg_lo:[1,1] neg_hi:[1,1]
	v_cvt_f32_i32_e32 v191, v83
	v_pk_fma_f32 v[146:147], v[172:173], v[152:153], v[146:147] neg_lo:[1,0,0] neg_hi:[1,0,0]
	v_max_f32_e32 v152, v166, v166
	v_max_f32_e32 v153, v167, v167
	v_max_f32_e32 v152, 0xda24260, v152
	v_max_f32_e32 v153, 0xda24260, v153
	v_pk_mul_f32 v[152:153], v[152:153], s[42:43] op_sel_hi:[1,0]
	v_cvt_f32_i32_e32 v190, v82
	v_div_scale_f32 v160, s[24:25], v152, v152, v156
	v_rcp_f32_e32 v161, v160
	v_pk_mul_f32 v[190:191], v[84:85], v[190:191] op_sel_hi:[0,1]
	v_mov_b32_e32 v192, v190
	v_mov_b32_e32 v193, v191
	v_fma_f32 v166, -v160, v161, 1.0
	v_fmac_f32_e32 v161, v166, v161
	v_div_scale_f32 v166, vcc, v156, v152, v156
	v_mul_f32_e32 v167, v166, v161
	v_fma_f32 v170, -v160, v167, v166
	v_fmac_f32_e32 v167, v170, v161
	v_fma_f32 v160, -v160, v167, v166
	v_div_fmas_f32 v160, v160, v161, v167
	v_div_fixup_f32 v203, v160, v152, v156
	v_div_scale_f32 v152, s[24:25], v153, v153, v157
	v_rcp_f32_e32 v156, v152
	v_mov_b32_dpp v192, v192 row_shr:1 row_mask:0xf bank_mask:0xf
	v_mov_b32_dpp v193, v193 row_shr:1 row_mask:0xf bank_mask:0xf
	v_cvt_f32_i32_e32 v167, v67
	v_fma_f32 v160, -v152, v156, 1.0
	v_fmac_f32_e32 v156, v160, v156
	v_div_scale_f32 v160, vcc, v157, v153, v157
	v_mul_f32_e32 v161, v160, v156
	v_fma_f32 v166, -v152, v161, v160
	v_fmac_f32_e32 v161, v166, v156
	v_fma_f32 v152, -v152, v161, v160
	v_div_fmas_f32 v152, v152, v156, v161
	v_div_fixup_f32 v204, v152, v153, v157
	v_cvt_f32_i32_e32 v153, v79
	v_cvt_f32_i32_e32 v152, v78
	v_cvt_f32_i32_e32 v157, v75
	v_cvt_f32_i32_e32 v156, v74
	v_cvt_f32_i32_e32 v161, v71
	v_pk_mul_f32 v[152:153], v[132:133], v[152:153] op_sel_hi:[0,1]
	v_pk_fma_f32 v[200:201], v[158:159], v[152:153], v[162:163]
	v_pk_mul_f32 v[156:157], v[132:133], v[156:157] op_sel:[1,0]
	v_cvt_f32_i32_e32 v160, v70
	v_cndmask_b32_e64 v199, v157, v204, s[8:9]
	v_cndmask_b32_e64 v198, v156, v203, s[8:9]
	v_pk_fma_f32 v[192:193], v[174:175], v[192:193], v[200:201]
	v_cvt_f32_i32_e32 v166, v66
	v_pk_fma_f32 v[192:193], v[154:155], v[198:199], v[192:193]
	v_mov_b32_e32 v194, v152
	v_pk_mul_f32 v[138:139], v[192:193], v[138:139]
	v_mov_b32_e32 v195, v153
	v_cvt_pk_fp8_f32 v197, v138, v139 op_sel:[0,0,1]
	s_nop 0
	v_cndmask_b32_e64 v139, v153, v204, s[10:11]
	v_cndmask_b32_e64 v138, v152, v203, s[10:11]
	v_pk_fma_f32 v[152:153], v[158:159], v[156:157], v[162:163]
	v_pk_mul_f32 v[160:161], v[134:135], v[160:161] op_sel_hi:[0,1]
	v_pk_fma_f32 v[138:139], v[174:175], v[138:139], v[152:153]
	v_pk_mul_f32 v[166:167], v[184:185], v[166:167] op_sel_hi:[0,1]
	v_pk_fma_f32 v[138:139], v[154:155], v[160:161], v[138:139]
	v_cvt_f32_i32_e32 v171, v95
	v_pk_mul_f32 v[138:139], v[138:139], v[142:143]
	v_pk_fma_f32 v[142:143], v[158:159], v[160:161], v[162:163]
	v_cvt_f32_i32_e32 v170, v94
	v_cvt_pk_fp8_f32 v187, v138, v139 op_sel:[0,0,1]
	s_nop 0
	v_cndmask_b32_e64 v139, v167, v204, s[12:13]
	v_cndmask_b32_e64 v138, v166, v203, s[12:13]
	v_pk_fma_f32 v[142:143], v[174:175], v[156:157], v[142:143]
	v_cvt_f32_i32_e32 v173, v91
	v_pk_fma_f32 v[138:139], v[154:155], v[138:139], v[142:143]
	v_cvt_f32_i32_e32 v172, v90
	v_pk_mul_f32 v[138:139], v[138:139], v[140:141]
	v_pk_fma_f32 v[140:141], v[158:159], v[166:167], v[162:163]
	v_cvt_pk_fp8_f32 v186, v138, v139 op_sel:[0,0,1]
	s_nop 0
	v_cndmask_b32_e64 v139, v161, v204, s[14:15]
	v_cndmask_b32_e64 v138, v160, v203, s[14:15]
	v_pk_mul_f32 v[170:171], v[128:129], v[170:171] op_sel_hi:[0,1]
	v_pk_fma_f32 v[138:139], v[174:175], v[138:139], v[140:141]
	v_pk_mul_f32 v[172:173], v[128:129], v[172:173] op_sel:[1,0]
	v_pk_fma_f32 v[138:139], v[154:155], v[170:171], v[138:139]
	v_pk_fma_f32 v[140:141], v[158:159], v[170:171], v[162:163]
	v_pk_mul_f32 v[138:139], v[138:139], v[144:145]
	v_cvt_f32_i32_e32 v189, v87
	v_cvt_f32_i32_e32 v188, v86
	v_cvt_pk_fp8_f32 v169, v138, v139 op_sel:[0,0,1]
	s_nop 0
	v_cndmask_b32_e64 v139, v173, v204, s[22:23]
	v_cndmask_b32_e64 v138, v172, v203, s[22:23]
	v_pk_fma_f32 v[140:141], v[174:175], v[166:167], v[140:141]
	v_pk_mul_f32 v[188:189], v[130:131], v[188:189] op_sel_hi:[0,1]
	v_pk_fma_f32 v[138:139], v[154:155], v[138:139], v[140:141]
	v_pk_fma_f32 v[140:141], v[158:159], v[172:173], v[162:163]
	v_pk_mul_f32 v[138:139], v[138:139], v[148:149]
	v_add_u32_e32 v84, -1, v185
	v_cvt_pk_fp8_f32 v168, v138, v139 op_sel:[0,0,1]
	s_nop 0
	v_cndmask_b32_e64 v139, v171, v204, s[20:21]
	v_cndmask_b32_e64 v138, v170, v203, s[20:21]
	v_pk_fma_f32 v[138:139], v[174:175], v[138:139], v[140:141]
	v_mov_b32_dpp v194, v194 row_shl:1 row_mask:0xf bank_mask:0xf
	v_pk_fma_f32 v[138:139], v[154:155], v[188:189], v[138:139]
	v_mov_b32_dpp v195, v195 row_shl:1 row_mask:0xf bank_mask:0xf
	v_pk_mul_f32 v[136:137], v[138:139], v[136:137]
	v_pk_fma_f32 v[138:139], v[158:159], v[188:189], v[162:163]
	v_cvt_pk_fp8_f32 v165, v136, v137 op_sel:[0,0,1]
	s_nop 0
	v_cndmask_b32_e64 v137, v191, v204, s[18:19]
	v_cndmask_b32_e64 v136, v190, v203, s[18:19]
	v_pk_fma_f32 v[138:139], v[174:175], v[172:173], v[138:139]
	v_cmp_gt_u32_e32 vcc, s87, v84
	v_pk_fma_f32 v[136:137], v[154:155], v[136:137], v[138:139]
	v_pk_fma_f32 v[138:139], v[158:159], v[190:191], v[162:163]
	v_pk_mul_f32 v[136:137], v[136:137], v[150:151]
	v_cmp_gt_i32_e64 s[24:25], s81, v85
	v_cvt_pk_fp8_f32 v164, v136, v137 op_sel:[0,0,1]
	s_nop 0
	v_cndmask_b32_e64 v137, v189, v204, s[16:17]
	v_cndmask_b32_e64 v136, v188, v203, s[16:17]
	v_pk_fma_f32 v[136:137], v[174:175], v[136:137], v[138:139]
	s_and_b64 s[42:43], vcc, s[24:25]
	v_pk_fma_f32 v[136:137], v[154:155], v[194:195], v[136:137]
	s_nop 0
	v_pk_mul_f32 v[136:137], v[136:137], v[146:147]
	s_nop 0
	v_cvt_pk_fp8_f32 v81, v136, v137 op_sel:[0,0,1]
	s_nop 0
	s_waitcnt vmcnt(0)
	s_and_saveexec_b64 s[24:25], s[42:43]
	s_cbranch_execz .LBB0_662
	s_movk_i32 s3, 0xb00
	v_mad_u64_u32 v[136:137], s[44:45], v85, s3, v[80:81]
	buffer_store_dword v197, v136, s[88:91], 0 offen
